# scan v3: y pairs exchanged between adjacent lanes (DPP+perm), one dword LDS write per two rows
# baseline (speedup 1.0000x reference)
; #define LAS __attribute__((address_space(3)))
; DI unsigned pk2(float a, float b) { f32x2 v = {a, b}; bf2_t r = __builtin_convertvector(v, bf2_t); return __builtin_bit_cast(unsigned, r); }
; DI void phase_rglru(const Params& p, unsigned char* shm) {
;     ...
;             if (tid < 192) {
; #pragma unroll 8
;                 for (int r = 0; r < 64; ++r) {
;                     const float om = __uint_as_float((unsigned)*(const LAS bf16_t*)(lds + LAo + r * TR + tid * 2) << 16);
;                     const float bt = __uint_as_float((unsigned)*(const LAS bf16_t*)(lds + BTo + r * TR + tid * 2) << 16);
;                     const float g = __uint_as_float((unsigned)*(const LAS bf16_t*)(lds + GT + r * TR + tid * 2) << 16);
;                     hst = (hst - om * hst) + bt;
;                     *(LAS bf16_t*)(lds + GT + r * TR + tid * 2) = (bf16_t)(pk2(hst * g, 0.f) & 0xffffu);
;                 }
.LBB0_851:
	s_andn2_saveexec_b64 s[2:3], s[2:3]
	s_cbranch_execz .LBB0_842
	v_mov_b32_e32 v126, 0
	v_mov_b32_e32 v127, 0
	v_mov_b32_e32 v128, 0
	v_mov_b32_e32 v129, 0
	v_mov_b32_e32 v130, 0
	v_mov_b32_e32 v131, 0
	v_mov_b32_e32 v132, 0
	v_mov_b32_e32 v133, 0
	v_mov_b32_e32 v134, 0
	v_mov_b32_e32 v135, 0
	v_mov_b32_e32 v136, 0
	v_mov_b32_e32 v137, 0
	v_mov_b32_e32 v138, 0
	v_mov_b32_e32 v139, 0
	v_mov_b32_e32 v140, 0
	v_mov_b32_e32 v141, 0
	v_mov_b32_e32 v142, 0
	v_mov_b32_e32 v143, 0
	v_mov_b32_e32 v144, 0
	v_mov_b32_e32 v145, 0
	v_mov_b32_e32 v146, 0
	v_mov_b32_e32 v147, 0
	v_mov_b32_e32 v148, 0
	v_mov_b32_e32 v149, 0
	v_add_u32_e32 v121, 0x13100, v176
	v_add_u32_e32 v122, 0x19500, v176
	v_add_u32_e32 v123, 0xcd00, v176
	v_and_b32_e32 v216, 2, v176
	v_cmp_eq_u32_e32 vcc, 0, v216
	v_mov_b32_e32 v214, 0x3020706
	v_mov_b32_e32 v213, 0x5040100
	v_cndmask_b32_e32 v214, v214, v213, vcc
	v_mul_u32_u24_e32 v215, 0xc8, v216
	v_sub_u32_e32 v216, v123, v216
	v_add_u32_e32 v215, v215, v216
	ds_read_u16_d16_hi v126, v121
	ds_read_u16_d16_hi v134, v122
	ds_read_u16_d16_hi v142, v123
	ds_read_u16_d16_hi v127, v121 offset:400
	ds_read_u16_d16_hi v135, v122 offset:400
	ds_read_u16_d16_hi v143, v123 offset:400
	ds_read_u16_d16_hi v128, v121 offset:800
	ds_read_u16_d16_hi v136, v122 offset:800
	ds_read_u16_d16_hi v144, v123 offset:800
	ds_read_u16_d16_hi v129, v121 offset:1200
	ds_read_u16_d16_hi v137, v122 offset:1200
	ds_read_u16_d16_hi v145, v123 offset:1200
	ds_read_u16_d16_hi v130, v121 offset:1600
	ds_read_u16_d16_hi v138, v122 offset:1600
	ds_read_u16_d16_hi v146, v123 offset:1600
	s_waitcnt lgkmcnt(12)
	v_fma_f32 v150, -v152, v126, v152
	v_add_f32_e32 v152, v150, v134
	v_mul_f32_e32 v170, v152, v142
	ds_read_u16_d16_hi v131, v121 offset:2000
	ds_read_u16_d16_hi v139, v122 offset:2000
	ds_read_u16_d16_hi v147, v123 offset:2000
	s_waitcnt lgkmcnt(12)
	v_fma_f32 v150, -v152, v127, v152
	v_add_f32_e32 v152, v150, v135
	v_mul_f32_e32 v171, v152, v143
	ds_read_u16_d16_hi v132, v121 offset:2400
	ds_read_u16_d16_hi v140, v122 offset:2400
	ds_read_u16_d16_hi v148, v123 offset:2400
	v_cvt_pk_bf16_f32 v210, v170, v171
	s_waitcnt lgkmcnt(12)
	v_fma_f32 v150, -v152, v128, v152
	v_add_f32_e32 v152, v150, v136
	v_mul_f32_e32 v170, v152, v144
	ds_read_u16_d16_hi v133, v121 offset:2800
	ds_read_u16_d16_hi v141, v122 offset:2800
	ds_read_u16_d16_hi v149, v123 offset:2800
	v_mov_b32_dpp v212, v210 quad_perm:[1,0,3,2] row_mask:0xf bank_mask:0xf
	v_perm_b32 v213, v212, v210, v214
	ds_write_b32 v215, v213
	s_waitcnt lgkmcnt(13)
	v_fma_f32 v150, -v152, v129, v152
	v_add_f32_e32 v152, v150, v137
	v_mul_f32_e32 v171, v152, v145
	ds_read_u16_d16_hi v126, v121 offset:3200
	ds_read_u16_d16_hi v134, v122 offset:3200
	ds_read_u16_d16_hi v142, v123 offset:3200
	v_cvt_pk_bf16_f32 v211, v170, v171
	s_waitcnt lgkmcnt(13)
	v_fma_f32 v150, -v152, v130, v152
	v_add_f32_e32 v152, v150, v138
	v_mul_f32_e32 v170, v152, v146
	ds_read_u16_d16_hi v127, v121 offset:3600
	ds_read_u16_d16_hi v135, v122 offset:3600
	ds_read_u16_d16_hi v143, v123 offset:3600
	v_mov_b32_dpp v212, v211 quad_perm:[1,0,3,2] row_mask:0xf bank_mask:0xf
	v_perm_b32 v213, v212, v211, v214
	ds_write_b32 v215, v213 offset:800
	s_waitcnt lgkmcnt(14)
	v_fma_f32 v150, -v152, v131, v152
	v_add_f32_e32 v152, v150, v139
	v_mul_f32_e32 v171, v152, v147
	ds_read_u16_d16_hi v128, v121 offset:4000
	ds_read_u16_d16_hi v136, v122 offset:4000
	ds_read_u16_d16_hi v144, v123 offset:4000
	v_cvt_pk_bf16_f32 v210, v170, v171
	s_waitcnt lgkmcnt(14)
	v_fma_f32 v150, -v152, v132, v152
	v_add_f32_e32 v152, v150, v140
	v_mul_f32_e32 v170, v152, v148
	ds_read_u16_d16_hi v129, v121 offset:4400
	ds_read_u16_d16_hi v137, v122 offset:4400
	ds_read_u16_d16_hi v145, v123 offset:4400
	v_mov_b32_dpp v212, v210 quad_perm:[1,0,3,2] row_mask:0xf bank_mask:0xf
	v_perm_b32 v213, v212, v210, v214
	ds_write_b32 v215, v213 offset:1600
	s_waitcnt lgkmcnt(15)
	v_fma_f32 v150, -v152, v133, v152
	v_add_f32_e32 v152, v150, v141
	v_mul_f32_e32 v171, v152, v149
	ds_read_u16_d16_hi v130, v121 offset:4800
	ds_read_u16_d16_hi v138, v122 offset:4800
	ds_read_u16_d16_hi v146, v123 offset:4800
	v_cvt_pk_bf16_f32 v211, v170, v171
	s_waitcnt lgkmcnt(14)
	v_fma_f32 v150, -v152, v126, v152
	v_add_f32_e32 v152, v150, v134
	v_mul_f32_e32 v170, v152, v142
	ds_read_u16_d16_hi v131, v121 offset:5200
	ds_read_u16_d16_hi v139, v122 offset:5200
	ds_read_u16_d16_hi v147, v123 offset:5200
	v_mov_b32_dpp v212, v211 quad_perm:[1,0,3,2] row_mask:0xf bank_mask:0xf
	v_perm_b32 v213, v212, v211, v214
	ds_write_b32 v215, v213 offset:2400
	s_waitcnt lgkmcnt(15)
	v_fma_f32 v150, -v152, v127, v152
	v_add_f32_e32 v152, v150, v135
	v_mul_f32_e32 v171, v152, v143
	ds_read_u16_d16_hi v132, v121 offset:5600
	ds_read_u16_d16_hi v140, v122 offset:5600
	ds_read_u16_d16_hi v148, v123 offset:5600
	v_cvt_pk_bf16_f32 v210, v170, v171
	s_waitcnt lgkmcnt(14)
	v_fma_f32 v150, -v152, v128, v152
	v_add_f32_e32 v152, v150, v136
	v_mul_f32_e32 v170, v152, v144
	ds_read_u16_d16_hi v133, v121 offset:6000
	ds_read_u16_d16_hi v141, v122 offset:6000
	ds_read_u16_d16_hi v149, v123 offset:6000
	v_mov_b32_dpp v212, v210 quad_perm:[1,0,3,2] row_mask:0xf bank_mask:0xf
	v_perm_b32 v213, v212, v210, v214
	ds_write_b32 v215, v213 offset:3200
	s_waitcnt lgkmcnt(15)
	v_fma_f32 v150, -v152, v129, v152
	v_add_f32_e32 v152, v150, v137
	v_mul_f32_e32 v171, v152, v145
	ds_read_u16_d16_hi v126, v121 offset:6400
	ds_read_u16_d16_hi v134, v122 offset:6400
	ds_read_u16_d16_hi v142, v123 offset:6400
	v_cvt_pk_bf16_f32 v211, v170, v171
	s_waitcnt lgkmcnt(14)
; #define LAS __attribute__((address_space(3)))
; DI unsigned pk2(float a, float b) { f32x2 v = {a, b}; bf2_t r = __builtin_convertvector(v, bf2_t); return __builtin_bit_cast(unsigned, r); }
; DI void phase_rglru(const Params& p, unsigned char* shm) {
;     ...
;             if (tid < 192) {
; #pragma unroll 8
;                 for (int r = 0; r < 64; ++r) {
;                     const float om = __uint_as_float((unsigned)*(const LAS bf16_t*)(lds + LAo + r * TR + tid * 2) << 16);
;                     const float bt = __uint_as_float((unsigned)*(const LAS bf16_t*)(lds + BTo + r * TR + tid * 2) << 16);
;                     const float g = __uint_as_float((unsigned)*(const LAS bf16_t*)(lds + GT + r * TR + tid * 2) << 16);
;                     hst = (hst - om * hst) + bt;
;                     *(LAS bf16_t*)(lds + GT + r * TR + tid * 2) = (bf16_t)(pk2(hst * g, 0.f) & 0xffffu);
;                 }
	v_fma_f32 v150, -v152, v130, v152
	v_add_f32_e32 v152, v150, v138
	v_mul_f32_e32 v170, v152, v146
	ds_read_u16_d16_hi v127, v121 offset:6800
	ds_read_u16_d16_hi v135, v122 offset:6800
	ds_read_u16_d16_hi v143, v123 offset:6800
	v_mov_b32_dpp v212, v211 quad_perm:[1,0,3,2] row_mask:0xf bank_mask:0xf
	v_perm_b32 v213, v212, v211, v214
	ds_write_b32 v215, v213 offset:4000
	s_waitcnt lgkmcnt(15)
	v_fma_f32 v150, -v152, v131, v152
	v_add_f32_e32 v152, v150, v139
	v_mul_f32_e32 v171, v152, v147
	ds_read_u16_d16_hi v128, v121 offset:7200
	ds_read_u16_d16_hi v136, v122 offset:7200
	ds_read_u16_d16_hi v144, v123 offset:7200
	v_cvt_pk_bf16_f32 v210, v170, v171
	s_waitcnt lgkmcnt(14)
	v_fma_f32 v150, -v152, v132, v152
	v_add_f32_e32 v152, v150, v140
	v_mul_f32_e32 v170, v152, v148
	ds_read_u16_d16_hi v129, v121 offset:7600
	ds_read_u16_d16_hi v137, v122 offset:7600
	ds_read_u16_d16_hi v145, v123 offset:7600
	v_mov_b32_dpp v212, v210 quad_perm:[1,0,3,2] row_mask:0xf bank_mask:0xf
	v_perm_b32 v213, v212, v210, v214
	ds_write_b32 v215, v213 offset:4800
	s_waitcnt lgkmcnt(15)
	v_fma_f32 v150, -v152, v133, v152
	v_add_f32_e32 v152, v150, v141
	v_mul_f32_e32 v171, v152, v149
	ds_read_u16_d16_hi v130, v121 offset:8000
	ds_read_u16_d16_hi v138, v122 offset:8000
	ds_read_u16_d16_hi v146, v123 offset:8000
	v_cvt_pk_bf16_f32 v211, v170, v171
	s_waitcnt lgkmcnt(14)
	v_fma_f32 v150, -v152, v126, v152
	v_add_f32_e32 v152, v150, v134
	v_mul_f32_e32 v170, v152, v142
	ds_read_u16_d16_hi v131, v121 offset:8400
	ds_read_u16_d16_hi v139, v122 offset:8400
	ds_read_u16_d16_hi v147, v123 offset:8400
	v_mov_b32_dpp v212, v211 quad_perm:[1,0,3,2] row_mask:0xf bank_mask:0xf
	v_perm_b32 v213, v212, v211, v214
	ds_write_b32 v215, v213 offset:5600
	s_waitcnt lgkmcnt(15)
	v_fma_f32 v150, -v152, v127, v152
	v_add_f32_e32 v152, v150, v135
	v_mul_f32_e32 v171, v152, v143
	ds_read_u16_d16_hi v132, v121 offset:8800
	ds_read_u16_d16_hi v140, v122 offset:8800
	ds_read_u16_d16_hi v148, v123 offset:8800
	v_cvt_pk_bf16_f32 v210, v170, v171
	s_waitcnt lgkmcnt(14)
	v_fma_f32 v150, -v152, v128, v152
	v_add_f32_e32 v152, v150, v136
	v_mul_f32_e32 v170, v152, v144
	ds_read_u16_d16_hi v133, v121 offset:9200
	ds_read_u16_d16_hi v141, v122 offset:9200
	ds_read_u16_d16_hi v149, v123 offset:9200
	v_mov_b32_dpp v212, v210 quad_perm:[1,0,3,2] row_mask:0xf bank_mask:0xf
	v_perm_b32 v213, v212, v210, v214
	ds_write_b32 v215, v213 offset:6400
	s_waitcnt lgkmcnt(15)
	v_fma_f32 v150, -v152, v129, v152
	v_add_f32_e32 v152, v150, v137
	v_mul_f32_e32 v171, v152, v145
	ds_read_u16_d16_hi v126, v121 offset:9600
	ds_read_u16_d16_hi v134, v122 offset:9600
	ds_read_u16_d16_hi v142, v123 offset:9600
	v_cvt_pk_bf16_f32 v211, v170, v171
	s_waitcnt lgkmcnt(14)
	v_fma_f32 v150, -v152, v130, v152
	v_add_f32_e32 v152, v150, v138
	v_mul_f32_e32 v170, v152, v146
	ds_read_u16_d16_hi v127, v121 offset:10000
	ds_read_u16_d16_hi v135, v122 offset:10000
	ds_read_u16_d16_hi v143, v123 offset:10000
	v_mov_b32_dpp v212, v211 quad_perm:[1,0,3,2] row_mask:0xf bank_mask:0xf
	v_perm_b32 v213, v212, v211, v214
	ds_write_b32 v215, v213 offset:7200
	s_waitcnt lgkmcnt(15)
	v_fma_f32 v150, -v152, v131, v152
	v_add_f32_e32 v152, v150, v139
	v_mul_f32_e32 v171, v152, v147
	ds_read_u16_d16_hi v128, v121 offset:10400
	ds_read_u16_d16_hi v136, v122 offset:10400
	ds_read_u16_d16_hi v144, v123 offset:10400
	v_cvt_pk_bf16_f32 v210, v170, v171
	s_waitcnt lgkmcnt(14)
	v_fma_f32 v150, -v152, v132, v152
	v_add_f32_e32 v152, v150, v140
	v_mul_f32_e32 v170, v152, v148
	ds_read_u16_d16_hi v129, v121 offset:10800
	ds_read_u16_d16_hi v137, v122 offset:10800
	ds_read_u16_d16_hi v145, v123 offset:10800
	v_mov_b32_dpp v212, v210 quad_perm:[1,0,3,2] row_mask:0xf bank_mask:0xf
	v_perm_b32 v213, v212, v210, v214
	ds_write_b32 v215, v213 offset:8000
	s_waitcnt lgkmcnt(15)
	v_fma_f32 v150, -v152, v133, v152
	v_add_f32_e32 v152, v150, v141
	v_mul_f32_e32 v171, v152, v149
	ds_read_u16_d16_hi v130, v121 offset:11200
	ds_read_u16_d16_hi v138, v122 offset:11200
	ds_read_u16_d16_hi v146, v123 offset:11200
	v_cvt_pk_bf16_f32 v211, v170, v171
	s_waitcnt lgkmcnt(14)
	v_fma_f32 v150, -v152, v126, v152
	v_add_f32_e32 v152, v150, v134
	v_mul_f32_e32 v170, v152, v142
	ds_read_u16_d16_hi v131, v121 offset:11600
	ds_read_u16_d16_hi v139, v122 offset:11600
	ds_read_u16_d16_hi v147, v123 offset:11600
	v_mov_b32_dpp v212, v211 quad_perm:[1,0,3,2] row_mask:0xf bank_mask:0xf
	v_perm_b32 v213, v212, v211, v214
	ds_write_b32 v215, v213 offset:8800
	s_waitcnt lgkmcnt(15)
	v_fma_f32 v150, -v152, v127, v152
	v_add_f32_e32 v152, v150, v135
	v_mul_f32_e32 v171, v152, v143
	ds_read_u16_d16_hi v132, v121 offset:12000
	ds_read_u16_d16_hi v140, v122 offset:12000
	ds_read_u16_d16_hi v148, v123 offset:12000
	v_cvt_pk_bf16_f32 v210, v170, v171
	s_waitcnt lgkmcnt(14)
	v_fma_f32 v150, -v152, v128, v152
	v_add_f32_e32 v152, v150, v136
	v_mul_f32_e32 v170, v152, v144
	ds_read_u16_d16_hi v133, v121 offset:12400
	ds_read_u16_d16_hi v141, v122 offset:12400
	ds_read_u16_d16_hi v149, v123 offset:12400
	v_mov_b32_dpp v212, v210 quad_perm:[1,0,3,2] row_mask:0xf bank_mask:0xf
	v_perm_b32 v213, v212, v210, v214
	ds_write_b32 v215, v213 offset:9600
	s_waitcnt lgkmcnt(15)
	v_fma_f32 v150, -v152, v129, v152
	v_add_f32_e32 v152, v150, v137
	v_mul_f32_e32 v171, v152, v145
	ds_read_u16_d16_hi v126, v121 offset:12800
	ds_read_u16_d16_hi v134, v122 offset:12800
	ds_read_u16_d16_hi v142, v123 offset:12800
	v_cvt_pk_bf16_f32 v211, v170, v171
	s_waitcnt lgkmcnt(14)
; #define LAS __attribute__((address_space(3)))
; DI unsigned pk2(float a, float b) { f32x2 v = {a, b}; bf2_t r = __builtin_convertvector(v, bf2_t); return __builtin_bit_cast(unsigned, r); }
; DI void phase_rglru(const Params& p, unsigned char* shm) {
;     ...
;             if (tid < 192) {
; #pragma unroll 8
;                 for (int r = 0; r < 64; ++r) {
;                     const float om = __uint_as_float((unsigned)*(const LAS bf16_t*)(lds + LAo + r * TR + tid * 2) << 16);
;                     const float bt = __uint_as_float((unsigned)*(const LAS bf16_t*)(lds + BTo + r * TR + tid * 2) << 16);
;                     const float g = __uint_as_float((unsigned)*(const LAS bf16_t*)(lds + GT + r * TR + tid * 2) << 16);
;                     hst = (hst - om * hst) + bt;
;                     *(LAS bf16_t*)(lds + GT + r * TR + tid * 2) = (bf16_t)(pk2(hst * g, 0.f) & 0xffffu);
;                 }
	v_fma_f32 v150, -v152, v130, v152
	v_add_f32_e32 v152, v150, v138
	v_mul_f32_e32 v170, v152, v146
	ds_read_u16_d16_hi v127, v121 offset:13200
	ds_read_u16_d16_hi v135, v122 offset:13200
	ds_read_u16_d16_hi v143, v123 offset:13200
	v_mov_b32_dpp v212, v211 quad_perm:[1,0,3,2] row_mask:0xf bank_mask:0xf
	v_perm_b32 v213, v212, v211, v214
	ds_write_b32 v215, v213 offset:10400
	s_waitcnt lgkmcnt(15)
	v_fma_f32 v150, -v152, v131, v152
	v_add_f32_e32 v152, v150, v139
	v_mul_f32_e32 v171, v152, v147
	ds_read_u16_d16_hi v128, v121 offset:13600
	ds_read_u16_d16_hi v136, v122 offset:13600
	ds_read_u16_d16_hi v144, v123 offset:13600
	v_cvt_pk_bf16_f32 v210, v170, v171
	s_waitcnt lgkmcnt(14)
	v_fma_f32 v150, -v152, v132, v152
	v_add_f32_e32 v152, v150, v140
	v_mul_f32_e32 v170, v152, v148
	ds_read_u16_d16_hi v129, v121 offset:14000
	ds_read_u16_d16_hi v137, v122 offset:14000
	ds_read_u16_d16_hi v145, v123 offset:14000
	v_mov_b32_dpp v212, v210 quad_perm:[1,0,3,2] row_mask:0xf bank_mask:0xf
	v_perm_b32 v213, v212, v210, v214
	ds_write_b32 v215, v213 offset:11200
	s_waitcnt lgkmcnt(15)
	v_fma_f32 v150, -v152, v133, v152
	v_add_f32_e32 v152, v150, v141
	v_mul_f32_e32 v171, v152, v149
	ds_read_u16_d16_hi v130, v121 offset:14400
	ds_read_u16_d16_hi v138, v122 offset:14400
	ds_read_u16_d16_hi v146, v123 offset:14400
	v_cvt_pk_bf16_f32 v211, v170, v171
	s_waitcnt lgkmcnt(14)
	v_fma_f32 v150, -v152, v126, v152
	v_add_f32_e32 v152, v150, v134
	v_mul_f32_e32 v170, v152, v142
	ds_read_u16_d16_hi v131, v121 offset:14800
	ds_read_u16_d16_hi v139, v122 offset:14800
	ds_read_u16_d16_hi v147, v123 offset:14800
	v_mov_b32_dpp v212, v211 quad_perm:[1,0,3,2] row_mask:0xf bank_mask:0xf
	v_perm_b32 v213, v212, v211, v214
	ds_write_b32 v215, v213 offset:12000
	s_waitcnt lgkmcnt(15)
	v_fma_f32 v150, -v152, v127, v152
	v_add_f32_e32 v152, v150, v135
	v_mul_f32_e32 v171, v152, v143
	ds_read_u16_d16_hi v132, v121 offset:15200
	ds_read_u16_d16_hi v140, v122 offset:15200
	ds_read_u16_d16_hi v148, v123 offset:15200
	v_cvt_pk_bf16_f32 v210, v170, v171
	s_waitcnt lgkmcnt(14)
	v_fma_f32 v150, -v152, v128, v152
	v_add_f32_e32 v152, v150, v136
	v_mul_f32_e32 v170, v152, v144
	ds_read_u16_d16_hi v133, v121 offset:15600
	ds_read_u16_d16_hi v141, v122 offset:15600
	ds_read_u16_d16_hi v149, v123 offset:15600
	v_mov_b32_dpp v212, v210 quad_perm:[1,0,3,2] row_mask:0xf bank_mask:0xf
	v_perm_b32 v213, v212, v210, v214
	ds_write_b32 v215, v213 offset:12800
	s_waitcnt lgkmcnt(15)
	v_fma_f32 v150, -v152, v129, v152
	v_add_f32_e32 v152, v150, v137
	v_mul_f32_e32 v171, v152, v145
	ds_read_u16_d16_hi v126, v121 offset:16000
	ds_read_u16_d16_hi v134, v122 offset:16000
	ds_read_u16_d16_hi v142, v123 offset:16000
	v_cvt_pk_bf16_f32 v211, v170, v171
	s_waitcnt lgkmcnt(14)
	v_fma_f32 v150, -v152, v130, v152
	v_add_f32_e32 v152, v150, v138
	v_mul_f32_e32 v170, v152, v146
	ds_read_u16_d16_hi v127, v121 offset:16400
	ds_read_u16_d16_hi v135, v122 offset:16400
	ds_read_u16_d16_hi v143, v123 offset:16400
	v_mov_b32_dpp v212, v211 quad_perm:[1,0,3,2] row_mask:0xf bank_mask:0xf
	v_perm_b32 v213, v212, v211, v214
	ds_write_b32 v215, v213 offset:13600
	s_waitcnt lgkmcnt(15)
	v_fma_f32 v150, -v152, v131, v152
	v_add_f32_e32 v152, v150, v139
	v_mul_f32_e32 v171, v152, v147
	ds_read_u16_d16_hi v128, v121 offset:16800
	ds_read_u16_d16_hi v136, v122 offset:16800
	ds_read_u16_d16_hi v144, v123 offset:16800
	v_cvt_pk_bf16_f32 v210, v170, v171
	s_waitcnt lgkmcnt(14)
	v_fma_f32 v150, -v152, v132, v152
	v_add_f32_e32 v152, v150, v140
	v_mul_f32_e32 v170, v152, v148
	ds_read_u16_d16_hi v129, v121 offset:17200
	ds_read_u16_d16_hi v137, v122 offset:17200
	ds_read_u16_d16_hi v145, v123 offset:17200
	v_mov_b32_dpp v212, v210 quad_perm:[1,0,3,2] row_mask:0xf bank_mask:0xf
	v_perm_b32 v213, v212, v210, v214
	ds_write_b32 v215, v213 offset:14400
	s_waitcnt lgkmcnt(15)
	v_fma_f32 v150, -v152, v133, v152
	v_add_f32_e32 v152, v150, v141
	v_mul_f32_e32 v171, v152, v149
	ds_read_u16_d16_hi v130, v121 offset:17600
	ds_read_u16_d16_hi v138, v122 offset:17600
	ds_read_u16_d16_hi v146, v123 offset:17600
	v_cvt_pk_bf16_f32 v211, v170, v171
	s_waitcnt lgkmcnt(14)
	v_fma_f32 v150, -v152, v126, v152
	v_add_f32_e32 v152, v150, v134
	v_mul_f32_e32 v170, v152, v142
	ds_read_u16_d16_hi v131, v121 offset:18000
	ds_read_u16_d16_hi v139, v122 offset:18000
	ds_read_u16_d16_hi v147, v123 offset:18000
	v_mov_b32_dpp v212, v211 quad_perm:[1,0,3,2] row_mask:0xf bank_mask:0xf
	v_perm_b32 v213, v212, v211, v214
	ds_write_b32 v215, v213 offset:15200
	s_waitcnt lgkmcnt(15)
	v_fma_f32 v150, -v152, v127, v152
	v_add_f32_e32 v152, v150, v135
	v_mul_f32_e32 v171, v152, v143
	ds_read_u16_d16_hi v132, v121 offset:18400
	ds_read_u16_d16_hi v140, v122 offset:18400
	ds_read_u16_d16_hi v148, v123 offset:18400
	v_cvt_pk_bf16_f32 v210, v170, v171
	s_waitcnt lgkmcnt(14)
	v_fma_f32 v150, -v152, v128, v152
	v_add_f32_e32 v152, v150, v136
	v_mul_f32_e32 v170, v152, v144
	ds_read_u16_d16_hi v133, v121 offset:18800
	ds_read_u16_d16_hi v141, v122 offset:18800
	ds_read_u16_d16_hi v149, v123 offset:18800
	v_mov_b32_dpp v212, v210 quad_perm:[1,0,3,2] row_mask:0xf bank_mask:0xf
	v_perm_b32 v213, v212, v210, v214
	ds_write_b32 v215, v213 offset:16000
	s_waitcnt lgkmcnt(15)
	v_fma_f32 v150, -v152, v129, v152
	v_add_f32_e32 v152, v150, v137
	v_mul_f32_e32 v171, v152, v145
	ds_read_u16_d16_hi v126, v121 offset:19200
	ds_read_u16_d16_hi v134, v122 offset:19200
	ds_read_u16_d16_hi v142, v123 offset:19200
	v_cvt_pk_bf16_f32 v211, v170, v171
	s_waitcnt lgkmcnt(14)
; #define LAS __attribute__((address_space(3)))
; DI unsigned pk2(float a, float b) { f32x2 v = {a, b}; bf2_t r = __builtin_convertvector(v, bf2_t); return __builtin_bit_cast(unsigned, r); }
; DI void phase_rglru(const Params& p, unsigned char* shm) {
;     ...
;             if (tid < 192) {
; #pragma unroll 8
;                 for (int r = 0; r < 64; ++r) {
;                     const float om = __uint_as_float((unsigned)*(const LAS bf16_t*)(lds + LAo + r * TR + tid * 2) << 16);
;                     const float bt = __uint_as_float((unsigned)*(const LAS bf16_t*)(lds + BTo + r * TR + tid * 2) << 16);
;                     const float g = __uint_as_float((unsigned)*(const LAS bf16_t*)(lds + GT + r * TR + tid * 2) << 16);
;                     hst = (hst - om * hst) + bt;
;                     *(LAS bf16_t*)(lds + GT + r * TR + tid * 2) = (bf16_t)(pk2(hst * g, 0.f) & 0xffffu);
;                 }
	v_fma_f32 v150, -v152, v130, v152
	v_add_f32_e32 v152, v150, v138
	v_mul_f32_e32 v170, v152, v146
	ds_read_u16_d16_hi v127, v121 offset:19600
	ds_read_u16_d16_hi v135, v122 offset:19600
	ds_read_u16_d16_hi v143, v123 offset:19600
	v_mov_b32_dpp v212, v211 quad_perm:[1,0,3,2] row_mask:0xf bank_mask:0xf
	v_perm_b32 v213, v212, v211, v214
	ds_write_b32 v215, v213 offset:16800
	s_waitcnt lgkmcnt(15)
	v_fma_f32 v150, -v152, v131, v152
	v_add_f32_e32 v152, v150, v139
	v_mul_f32_e32 v171, v152, v147
	ds_read_u16_d16_hi v128, v121 offset:20000
	ds_read_u16_d16_hi v136, v122 offset:20000
	ds_read_u16_d16_hi v144, v123 offset:20000
	v_cvt_pk_bf16_f32 v210, v170, v171
	s_waitcnt lgkmcnt(14)
	v_fma_f32 v150, -v152, v132, v152
	v_add_f32_e32 v152, v150, v140
	v_mul_f32_e32 v170, v152, v148
	ds_read_u16_d16_hi v129, v121 offset:20400
	ds_read_u16_d16_hi v137, v122 offset:20400
	ds_read_u16_d16_hi v145, v123 offset:20400
	v_mov_b32_dpp v212, v210 quad_perm:[1,0,3,2] row_mask:0xf bank_mask:0xf
	v_perm_b32 v213, v212, v210, v214
	ds_write_b32 v215, v213 offset:17600
	s_waitcnt lgkmcnt(15)
	v_fma_f32 v150, -v152, v133, v152
	v_add_f32_e32 v152, v150, v141
	v_mul_f32_e32 v171, v152, v149
	ds_read_u16_d16_hi v130, v121 offset:20800
	ds_read_u16_d16_hi v138, v122 offset:20800
	ds_read_u16_d16_hi v146, v123 offset:20800
	v_cvt_pk_bf16_f32 v211, v170, v171
	s_waitcnt lgkmcnt(14)
	v_fma_f32 v150, -v152, v126, v152
	v_add_f32_e32 v152, v150, v134
	v_mul_f32_e32 v170, v152, v142
	ds_read_u16_d16_hi v131, v121 offset:21200
	ds_read_u16_d16_hi v139, v122 offset:21200
	ds_read_u16_d16_hi v147, v123 offset:21200
	v_mov_b32_dpp v212, v211 quad_perm:[1,0,3,2] row_mask:0xf bank_mask:0xf
	v_perm_b32 v213, v212, v211, v214
	ds_write_b32 v215, v213 offset:18400
	s_waitcnt lgkmcnt(15)
	v_fma_f32 v150, -v152, v127, v152
	v_add_f32_e32 v152, v150, v135
	v_mul_f32_e32 v171, v152, v143
	ds_read_u16_d16_hi v132, v121 offset:21600
	ds_read_u16_d16_hi v140, v122 offset:21600
	ds_read_u16_d16_hi v148, v123 offset:21600
	v_cvt_pk_bf16_f32 v210, v170, v171
	s_waitcnt lgkmcnt(14)
	v_fma_f32 v150, -v152, v128, v152
	v_add_f32_e32 v152, v150, v136
	v_mul_f32_e32 v170, v152, v144
	ds_read_u16_d16_hi v133, v121 offset:22000
	ds_read_u16_d16_hi v141, v122 offset:22000
	ds_read_u16_d16_hi v149, v123 offset:22000
	v_mov_b32_dpp v212, v210 quad_perm:[1,0,3,2] row_mask:0xf bank_mask:0xf
	v_perm_b32 v213, v212, v210, v214
	ds_write_b32 v215, v213 offset:19200
	s_waitcnt lgkmcnt(15)
	v_fma_f32 v150, -v152, v129, v152
	v_add_f32_e32 v152, v150, v137
	v_mul_f32_e32 v171, v152, v145
	ds_read_u16_d16_hi v126, v121 offset:22400
	ds_read_u16_d16_hi v134, v122 offset:22400
	ds_read_u16_d16_hi v142, v123 offset:22400
	v_cvt_pk_bf16_f32 v211, v170, v171
	s_waitcnt lgkmcnt(14)
	v_fma_f32 v150, -v152, v130, v152
	v_add_f32_e32 v152, v150, v138
	v_mul_f32_e32 v170, v152, v146
	ds_read_u16_d16_hi v127, v121 offset:22800
	ds_read_u16_d16_hi v135, v122 offset:22800
	ds_read_u16_d16_hi v143, v123 offset:22800
	v_mov_b32_dpp v212, v211 quad_perm:[1,0,3,2] row_mask:0xf bank_mask:0xf
	v_perm_b32 v213, v212, v211, v214
	ds_write_b32 v215, v213 offset:20000
	s_waitcnt lgkmcnt(15)
	v_fma_f32 v150, -v152, v131, v152
	v_add_f32_e32 v152, v150, v139
	v_mul_f32_e32 v171, v152, v147
	ds_read_u16_d16_hi v128, v121 offset:23200
	ds_read_u16_d16_hi v136, v122 offset:23200
	ds_read_u16_d16_hi v144, v123 offset:23200
	v_cvt_pk_bf16_f32 v210, v170, v171
	s_waitcnt lgkmcnt(14)
	v_fma_f32 v150, -v152, v132, v152
	v_add_f32_e32 v152, v150, v140
	v_mul_f32_e32 v170, v152, v148
	ds_read_u16_d16_hi v129, v121 offset:23600
	ds_read_u16_d16_hi v137, v122 offset:23600
	ds_read_u16_d16_hi v145, v123 offset:23600
	v_mov_b32_dpp v212, v210 quad_perm:[1,0,3,2] row_mask:0xf bank_mask:0xf
	v_perm_b32 v213, v212, v210, v214
	ds_write_b32 v215, v213 offset:20800
	s_waitcnt lgkmcnt(15)
	v_fma_f32 v150, -v152, v133, v152
	v_add_f32_e32 v152, v150, v141
	v_mul_f32_e32 v171, v152, v149
	ds_read_u16_d16_hi v130, v121 offset:24000
	ds_read_u16_d16_hi v138, v122 offset:24000
	ds_read_u16_d16_hi v146, v123 offset:24000
	v_cvt_pk_bf16_f32 v211, v170, v171
	s_waitcnt lgkmcnt(14)
	v_fma_f32 v150, -v152, v126, v152
	v_add_f32_e32 v152, v150, v134
	v_mul_f32_e32 v170, v152, v142
	ds_read_u16_d16_hi v131, v121 offset:24400
	ds_read_u16_d16_hi v139, v122 offset:24400
	ds_read_u16_d16_hi v147, v123 offset:24400
	v_mov_b32_dpp v212, v211 quad_perm:[1,0,3,2] row_mask:0xf bank_mask:0xf
	v_perm_b32 v213, v212, v211, v214
	ds_write_b32 v215, v213 offset:21600
	s_waitcnt lgkmcnt(15)
	v_fma_f32 v150, -v152, v127, v152
	v_add_f32_e32 v152, v150, v135
	v_mul_f32_e32 v171, v152, v143
	ds_read_u16_d16_hi v132, v121 offset:24800
	ds_read_u16_d16_hi v140, v122 offset:24800
	ds_read_u16_d16_hi v148, v123 offset:24800
	v_cvt_pk_bf16_f32 v210, v170, v171
	s_waitcnt lgkmcnt(14)
	v_fma_f32 v150, -v152, v128, v152
	v_add_f32_e32 v152, v150, v136
	v_mul_f32_e32 v170, v152, v144
	ds_read_u16_d16_hi v133, v121 offset:25200
	ds_read_u16_d16_hi v141, v122 offset:25200
	ds_read_u16_d16_hi v149, v123 offset:25200
	v_mov_b32_dpp v212, v210 quad_perm:[1,0,3,2] row_mask:0xf bank_mask:0xf
	v_perm_b32 v213, v212, v210, v214
	ds_write_b32 v215, v213 offset:22400
	s_waitcnt lgkmcnt(15)
	v_fma_f32 v150, -v152, v129, v152
	v_add_f32_e32 v152, v150, v137
	v_mul_f32_e32 v171, v152, v145
	v_cvt_pk_bf16_f32 v211, v170, v171
	s_waitcnt lgkmcnt(11)
	v_fma_f32 v150, -v152, v130, v152
	v_add_f32_e32 v152, v150, v138
	v_mul_f32_e32 v170, v152, v146
	v_mov_b32_dpp v212, v211 quad_perm:[1,0,3,2] row_mask:0xf bank_mask:0xf
	v_perm_b32 v213, v212, v211, v214
	ds_write_b32 v215, v213 offset:23200
	s_waitcnt lgkmcnt(9)
	v_fma_f32 v150, -v152, v131, v152
	v_add_f32_e32 v152, v150, v139
	v_mul_f32_e32 v171, v152, v147
	v_cvt_pk_bf16_f32 v210, v170, v171
	s_waitcnt lgkmcnt(5)
	v_fma_f32 v150, -v152, v132, v152
	v_add_f32_e32 v152, v150, v140
	v_mul_f32_e32 v170, v152, v148
	v_mov_b32_dpp v212, v210 quad_perm:[1,0,3,2] row_mask:0xf bank_mask:0xf
	v_perm_b32 v213, v212, v210, v214
	ds_write_b32 v215, v213 offset:24000
	s_waitcnt lgkmcnt(3)
	v_fma_f32 v150, -v152, v133, v152
	v_add_f32_e32 v152, v150, v141
	v_mul_f32_e32 v171, v152, v149
	v_cvt_pk_bf16_f32 v211, v170, v171
	s_nop 1
	v_mov_b32_dpp v212, v211 quad_perm:[1,0,3,2] row_mask:0xf bank_mask:0xf
	v_perm_b32 v213, v212, v211, v214
	ds_write_b32 v215, v213 offset:24800
	s_branch .LBB0_842
